# branch-projection (gate) epilogue: accumulators and row/column terms exchanged between lanes (as in FF2) so gate / partial loads and merged stores touch one row per four lanes
# baseline (speedup 1.0000x reference)
; __device__ __forceinline__ int otid() { int t = threadIdx.x; asm volatile("" : "+v"(t)); return t; }
; #define PG8_STAGE(bufoff, gbase, voff) do { _Pragma("unroll") for (int _i = 0; _i < 2; ++_i) \
;     __builtin_amdgcn_global_load_lds((const unsigned*)((const char*)(gbase) + (voff)[_i]), (LAS unsigned*)(lds + (bufoff) + ldsw + _i * 8192), 16, 0, 0); } while (0)
; #define PG8_WAIT_V(n) asm volatile("s_waitcnt vmcnt(" #n ")" ::: "memory")
; #define PG8_BAR __builtin_amdgcn_s_barrier()
; template <class Epi>
; __device__ __forceinline__ void gemm_phase(LAS unsigned char* lds, const Gemm g, const StaticOrder& S, const Epi& E) {
;   const int tid = otid(), wid = __builtin_amdgcn_readfirstlane(tid >> 6), lane = tid & 63, wr = wid >> 2, wc = wid & 3, fr = lane & 15, fq = lane >> 4;
;   const int K = g.K;
;   unsigned voffA[2], voffB[2];
; #pragma unroll
;   for (int i = 0; i < 2; ++i) {
;     int R, C;
;     stage_rc(tid * 16 + i * 8192, R, C);
;     const int Rb = Epi::PERM ? ((R & ~31) + perm32(R & 31)) : R;
;     voffA[i] = (unsigned)(R * g.lda + C) * 2u;
;     voffB[i] = (unsigned)(Rb * g.ldb + C) * 2u;
;   }
;   const size_t kstep = (size_t)(BK * 2);
;   const size_t hstepA = (size_t)HALF * g.lda * 2, hstepB = (size_t)HALF * g.ldb * 2;
;   const size_t tstepA = 2 * hstepA, tstepB = 2 * hstepB;
;   const unsigned ldsw = (unsigned)wid * 1024u;
;   const int aoff = lds_byte(wr * 64 + fr, fq * 8), boff = lds_byte(wc * 32 + fr, fq * 8);
;     ...
;   const char* cA = (const char*)(cur.which ? g.A2 : g.A) + (size_t)cur.pm * tstepA + (size_t)cur.kt0 * kstep;
;   const char* cB = (const char*)(cur.which ? g.Bt2 : g.Bt) + (size_t)cur.pn * tstepB + (size_t)cur.kt0 * kstep;
;   PG8_STAGE(PG8_SB(0, 0), cB, voffB); PG8_STAGE(PG8_SA(0, 0), cA, voffA); PG8_STAGE(PG8_SB(0, 1), cB + hstepB, voffB); PG8_STAGE(PG8_SA(0, 1), cA + hstepA, voffA);
;   if (wr == 1) PG8_BAR;
;   PG8_WAIT_V(4); PG8_BAR;
;   PG8_STAGE(PG8_SB(1, 0), cB + kstep, voffB); PG8_STAGE(PG8_SA(1, 0), cA + kstep, voffA); PG8_STAGE(PG8_SB(1, 1), cB + hstepB + kstep, voffB);
;   PG8_WAIT_V(6); PG8_BAR;
.LBB0_3527:
	s_add_u32 s38, s2, 0xc822000
	s_addc_u32 s39, s3, 0
	s_lshl_b32 s6, s6, 1
	s_add_u32 s6, s2, s6
	s_addc_u32 s7, s3, 0
	s_add_u32 s40, s6, 0x1300000
	s_addc_u32 s41, s7, 0
	s_lshl_b32 s1, s1, 5
	s_and_b32 s1, s1, 0x60
	s_add_i32 m0, s34, 0x18000
	v_lshl_add_u64 v[6:7], v[6:7], 0, s[16:17]
	s_lshl_b32 s8, s0, 13
	s_lshl_b32 s9, s1, 7
	s_waitcnt vmcnt(4)
	s_barrier
	global_load_lds_dwordx4 v[6:7], off
	v_lshl_add_u64 v[4:5], v[4:5], 0, s[16:17]
	s_add_i32 m0, s34, 0x1a000
	s_add_i32 s42, s34, 0x8000
	s_add_i32 s43, s34, 0xa000
	global_load_lds_dwordx4 v[4:5], off
	v_lshl_add_u64 v[2:3], v[2:3], 0, s[16:17]
	s_mov_b32 m0, s42
	s_add_u32 s6, s20, 0x20080
	global_load_lds_dwordx4 v[2:3], off
	v_lshl_add_u64 v[0:1], v[0:1], 0, s[16:17]
	s_mov_b32 m0, s43
	s_addc_u32 s7, s21, 0
	global_load_lds_dwordx4 v[0:1], off
	s_add_i32 m0, s34, 0x1c000
	v_lshl_add_u64 v[0:1], s[6:7], 0, v[168:169]
	global_load_lds_dwordx4 v[0:1], off
	v_lshl_add_u64 v[0:1], s[6:7], 0, v[164:165]
	s_add_i32 m0, s34, 0x1e000
	v_readlane_b32 s6, v255, 20
	global_load_lds_dwordx4 v[0:1], off
	v_lshrrev_b32_e32 v0, 1, v8
	v_and_b32_e32 v0, 24, v0
	v_and_b32_e32 v1, 15, v8
	v_lshlrev_b32_e32 v2, 1, v0
	v_lshl_or_b32 v173, s0, 6, v1
	v_lshl_or_b32 v1, v1, 6, v2
	v_lshlrev_b32_e32 v2, 2, v8
	v_and_b32_e32 v2, 32, v2
	v_bitop3_b32 v3, v1, s8, v2 bitop3:0xde
	v_bitop3_b32 v196, v1, s9, v2 bitop3:0xde
	v_lshlrev_b32_e32 v1, 13, v13
	v_and_b32_e32 v1, 0xffffc000, v1
	v_lshl_add_u32 v1, v12, 10, v1
	v_and_b32_e32 v2, 1, v13
	v_lshl_or_b32 v1, v2, 6, v1
	v_lshl_add_u32 v174, v14, 1, v1
	v_lshlrev_b32_e32 v1, 13, v9
	v_and_b32_e32 v1, 0xffffc000, v1
	s_waitcnt vmcnt(6)
	v_lshl_add_u32 v1, v10, 10, v1
	v_and_b32_e32 v2, 1, v9
	v_readlane_b32 s7, v255, 21
	s_lshl_b32 s6, s1, 1
	v_or_b32_e32 v172, s1, v0
	v_lshl_or_b32 v1, v2, 6, v1
	v_writelane_b32 v255, s6, 20
	v_readlane_b32 s0, v254, 62
	v_or_b32_e32 v197, 16, v173
	v_or_b32_e32 v202, 32, v173
	v_or_b32_e32 v203, 48, v173
	v_mov_b32_e32 v175, v17
	v_lshl_add_u32 v176, v11, 1, v1
	v_mov_b32_e32 v177, v17
	s_mov_b32 s48, 0
	v_add_u32_e32 v204, 0, v3
	v_writelane_b32 v255, s7, 21
	v_lshlrev_b32_e32 v16, 1, v0
	v_and_b32_e32 v0, 3, v252
	v_lshlrev_b32_e32 v0, 4, v0
	v_and_b32_e32 v1, 12, v252
	v_bfe_u32 v2, v252, 4, 2
	v_or3_b32 v0, v0, v1, v2
	v_lshlrev_b32_e32 v0, 2, v0
	ds_bpermute_b32 v173, v0, v173
	ds_bpermute_b32 v197, v0, v197
	ds_bpermute_b32 v202, v0, v202
	ds_bpermute_b32 v203, v0, v203
	ds_bpermute_b32 v172, v0, v172
	ds_bpermute_b32 v16, v0, v16
	s_waitcnt lgkmcnt(0)
	v_readlane_b32 s46, v254, 33
	s_mov_b32 s47, s0
	s_mov_b32 s44, 0
	s_barrier
	v_readlane_b32 s1, v254, 63
	s_branch .LBB0_3529

; #define PG8_STAGE(bufoff, gbase, voff) do { _Pragma("unroll") for (int _i = 0; _i < 2; ++_i) \
;     __builtin_amdgcn_global_load_lds((const unsigned*)((const char*)(gbase) + (voff)[_i]), (LAS unsigned*)(lds + (bufoff) + ldsw + _i * 8192), 16, 0, 0); } while (0)
; #define PG8_LDA(dst, b, h) do { _Pragma("unroll") for (int m = 0; m < 4; ++m) _Pragma("unroll") for (int k = 0; k < 2; ++k) dst[m][k] = *(const LAS bf16x8*)(lds + PG8_SA(b, h) + aoff + m * 2048 + k * 1024); } while (0)
; #define PG8_LDB(dst, b, h) do { _Pragma("unroll") for (int n = 0; n < 2; ++n) _Pragma("unroll") for (int k = 0; k < 2; ++k) dst[n][k] = *(const LAS bf16x8*)(lds + PG8_SB(b, h) + boff + n * 2048 + k * 1024); } while (0)
; #define PG8_MMA(ai, bj, At, Bt) do { __builtin_amdgcn_s_setprio(1); _Pragma("unroll") for (int m = 0; m < 4; ++m) _Pragma("unroll") for (int n = 0; n < 2; ++n) _Pragma("unroll") for (int k = 0; k < 2; ++k) \
;     acc[ai][bj][m][n] = __builtin_amdgcn_mfma_f32_16x16x32_bf16(Bt[n][k], At[m][k], acc[ai][bj][m][n], 0, 0, 0); __builtin_amdgcn_s_setprio(0); } while (0)
; #define PG8_WAIT_V(n) asm volatile("s_waitcnt vmcnt(" #n ")" ::: "memory")
; #define PG8_WAIT_L(n) asm volatile("s_waitcnt lgkmcnt(" #n ")" ::: "memory")
; #define PG8_BAR __builtin_amdgcn_s_barrier()
; #define PG8_SCHED __builtin_amdgcn_sched_barrier(0)
; template <class Epi>
; __device__ __forceinline__ void gemm_phase(LAS unsigned char* lds, const Gemm g, const StaticOrder& S, const Epi& E) {
;     ...
;       PG8_LDB(B0, 0, 0); PG8_SCHED; PG8_LDA(At, 0, 0); PG8_STAGE(PG8_SA(1, 1), a1 + hstepA, voffA);
;       PG8_WAIT_L(8); PG8_BAR; PG8_WAIT_L(0); PG8_MMA(0, 0, At, B0); PG8_BAR; PG8_SCHED;
;       PG8_LDB(B1, 0, 1); PG8_STAGE(PG8_SB(0, 0), b2, voffB);
;       PG8_BAR; PG8_WAIT_L(0); PG8_MMA(0, 1, At, B1); PG8_BAR;
;       PG8_LDA(At, 0, 1); PG8_STAGE(PG8_SA(0, 0), a2, voffA);
;       PG8_BAR; PG8_WAIT_L(0); PG8_MMA(1, 0, At, B0); PG8_BAR; PG8_SCHED;
;       PG8_STAGE(PG8_SB(0, 1), b2 + hstepB, voffB);
;       PG8_WAIT_V(6); PG8_BAR; PG8_MMA(1, 1, At, B1); PG8_BAR;
.LBB0_3542:
	s_add_u32 s20, s0, 0xfffe0080
	s_addc_u32 s21, s1, -1
	s_add_i32 s25, 0, 0x10000
	v_add_u32_e32 v142, s25, v196
	ds_read_b128 v[130:133], v142
	ds_read_b128 v[134:137], v142 offset:1024
	ds_read_b128 v[138:141], v142 offset:2048
	ds_read_b128 v[142:145], v142 offset:3072
	s_cmp_eq_u32 s24, 4
	s_cselect_b32 s23, s13, s21
	s_cselect_b32 s22, s12, s20
	s_cselect_b32 s21, s15, s9
	s_cselect_b32 s20, s14, s7
	v_lshl_add_u64 v[162:163], s[0:1], 0, v[174:175]
	s_add_i32 m0, s34, 0xc000
	ds_read_b128 v[146:149], v204
	ds_read_b128 v[150:153], v204 offset:1024
	ds_read_b128 v[154:157], v204 offset:2048
	ds_read_b128 v[158:161], v204 offset:3072
	ds_read_b128 v[178:181], v204 offset:4096
	ds_read_b128 v[182:185], v204 offset:5120
	ds_read_b128 v[186:189], v204 offset:6144
	ds_read_b128 v[190:193], v204 offset:7168
	global_load_lds_dwordx4 v[162:163], off
	v_lshl_add_u64 v[162:163], s[0:1], 0, v[176:177]
	s_add_i32 m0, s34, 0xe000
	s_nop 0
	global_load_lds_dwordx4 v[162:163], off
	s_waitcnt lgkmcnt(8)
	s_barrier
	s_waitcnt lgkmcnt(0)
	s_setprio 1
	s_waitcnt lgkmcnt(0)
	v_mfma_f32_16x16x32_bf16 v[126:129], v[130:133], v[146:149], v[126:129]
	v_mfma_f32_16x16x32_bf16 v[122:125], v[138:141], v[146:149], v[122:125]
	v_mfma_f32_16x16x32_bf16 v[110:113], v[130:133], v[154:157], v[110:113]
	v_mfma_f32_16x16x32_bf16 v[106:109], v[138:141], v[154:157], v[106:109]
	v_mfma_f32_16x16x32_bf16 v[94:97], v[130:133], v[178:181], v[94:97]
	v_mfma_f32_16x16x32_bf16 v[90:93], v[138:141], v[178:181], v[90:93]
	v_mfma_f32_16x16x32_bf16 v[78:81], v[130:133], v[186:189], v[78:81]
	v_mfma_f32_16x16x32_bf16 v[74:77], v[138:141], v[186:189], v[74:77]
	v_mfma_f32_16x16x32_bf16 v[126:129], v[134:137], v[150:153], v[126:129]
	v_mfma_f32_16x16x32_bf16 v[122:125], v[142:145], v[150:153], v[122:125]
	v_mfma_f32_16x16x32_bf16 v[110:113], v[134:137], v[158:161], v[110:113]
	v_mfma_f32_16x16x32_bf16 v[106:109], v[142:145], v[158:161], v[106:109]
	v_mfma_f32_16x16x32_bf16 v[94:97], v[134:137], v[182:185], v[94:97]
	v_mfma_f32_16x16x32_bf16 v[90:93], v[142:145], v[182:185], v[90:93]
	v_mfma_f32_16x16x32_bf16 v[78:81], v[134:137], v[190:193], v[78:81]
	v_mfma_f32_16x16x32_bf16 v[74:77], v[142:145], v[190:193], v[74:77]
	s_setprio 0
	s_barrier
	s_add_i32 s49, 0, 0x14000
	v_add_u32_e32 v162, s49, v196
	s_add_i32 s25, s25, s31
	ds_read_b128 v[198:201], v162
	ds_read_b128 v[206:209], v162 offset:1024
	ds_read_b128 v[210:213], v162 offset:2048
	ds_read_b128 v[214:217], v162 offset:3072
	v_lshl_add_u64 v[162:163], s[20:21], 0, v[168:169]
	s_mov_b32 m0, s25
	v_lshl_add_u64 v[194:195], s[20:21], 0, v[164:165]
	global_load_lds_dwordx4 v[162:163], off
	s_add_i32 m0, s25, 0x2000
	s_nop 0
	global_load_lds_dwordx4 v[194:195], off
	s_barrier
	s_waitcnt lgkmcnt(0)
	s_setprio 1
	s_waitcnt lgkmcnt(0)
	v_mfma_f32_16x16x32_bf16 v[118:121], v[198:201], v[146:149], v[118:121]
	v_mfma_f32_16x16x32_bf16 v[114:117], v[210:213], v[146:149], v[114:117]
	v_mfma_f32_16x16x32_bf16 v[102:105], v[198:201], v[154:157], v[102:105]
	v_mfma_f32_16x16x32_bf16 v[98:101], v[210:213], v[154:157], v[98:101]
	v_mfma_f32_16x16x32_bf16 v[86:89], v[198:201], v[178:181], v[86:89]
	v_mfma_f32_16x16x32_bf16 v[82:85], v[210:213], v[178:181], v[82:85]
	v_mfma_f32_16x16x32_bf16 v[70:73], v[198:201], v[186:189], v[70:73]
	v_mfma_f32_16x16x32_bf16 v[66:69], v[210:213], v[186:189], v[66:69]
	v_mfma_f32_16x16x32_bf16 v[118:121], v[206:209], v[150:153], v[118:121]
	v_mfma_f32_16x16x32_bf16 v[114:117], v[214:217], v[150:153], v[114:117]
	v_mfma_f32_16x16x32_bf16 v[102:105], v[206:209], v[158:161], v[102:105]
	v_mfma_f32_16x16x32_bf16 v[98:101], v[214:217], v[158:161], v[98:101]
	v_mfma_f32_16x16x32_bf16 v[86:89], v[206:209], v[182:185], v[86:89]
	v_mfma_f32_16x16x32_bf16 v[82:85], v[214:217], v[182:185], v[82:85]
	v_mfma_f32_16x16x32_bf16 v[70:73], v[206:209], v[190:193], v[70:73]
	v_mfma_f32_16x16x32_bf16 v[66:69], v[214:217], v[190:193], v[66:69]
	s_setprio 0
	s_mov_b32 m0, s34
	v_lshl_add_u64 v[218:219], s[22:23], 0, v[170:171]
	s_barrier
	ds_read_b128 v[146:149], v204 offset:16384
	ds_read_b128 v[150:153], v204 offset:17408
	ds_read_b128 v[154:157], v204 offset:18432
	ds_read_b128 v[158:161], v204 offset:19456
	ds_read_b128 v[178:181], v204 offset:20480
	ds_read_b128 v[182:185], v204 offset:21504
	ds_read_b128 v[186:189], v204 offset:22528
	ds_read_b128 v[190:193], v204 offset:23552
	global_load_lds_dwordx4 v[218:219], off
	v_lshl_add_u64 v[220:221], s[22:23], 0, v[166:167]
	s_mov_b32 m0, s35
	s_nop 0
	global_load_lds_dwordx4 v[220:221], off
	s_barrier
	s_waitcnt lgkmcnt(0)
	s_setprio 1
	s_waitcnt lgkmcnt(0)
	v_mfma_f32_16x16x32_bf16 v[62:65], v[130:133], v[146:149], v[62:65]
	v_mfma_f32_16x16x32_bf16 v[58:61], v[138:141], v[146:149], v[58:61]
	v_mfma_f32_16x16x32_bf16 v[46:49], v[130:133], v[154:157], v[46:49]
	v_mfma_f32_16x16x32_bf16 v[42:45], v[138:141], v[154:157], v[42:45]
	v_mfma_f32_16x16x32_bf16 v[30:33], v[130:133], v[178:181], v[30:33]
	v_mfma_f32_16x16x32_bf16 v[26:29], v[138:141], v[178:181], v[26:29]
	v_mfma_f32_16x16x32_bf16 v[12:15], v[130:133], v[186:189], v[12:15]
	v_mfma_f32_16x16x32_bf16 v[8:11], v[138:141], v[186:189], v[8:11]
	v_mfma_f32_16x16x32_bf16 v[62:65], v[134:137], v[150:153], v[62:65]
	v_mfma_f32_16x16x32_bf16 v[58:61], v[142:145], v[150:153], v[58:61]
	v_mfma_f32_16x16x32_bf16 v[46:49], v[134:137], v[158:161], v[46:49]
	v_mfma_f32_16x16x32_bf16 v[42:45], v[142:145], v[158:161], v[42:45]
	v_mfma_f32_16x16x32_bf16 v[30:33], v[134:137], v[182:185], v[30:33]
	v_mfma_f32_16x16x32_bf16 v[26:29], v[142:145], v[182:185], v[26:29]
	v_mfma_f32_16x16x32_bf16 v[12:15], v[134:137], v[190:193], v[12:15]
	v_mfma_f32_16x16x32_bf16 v[8:11], v[142:145], v[190:193], v[8:11]
	s_setprio 0
	s_barrier
; #define PG8_STAGE(bufoff, gbase, voff) do { _Pragma("unroll") for (int _i = 0; _i < 2; ++_i) \
;     __builtin_amdgcn_global_load_lds((const unsigned*)((const char*)(gbase) + (voff)[_i]), (LAS unsigned*)(lds + (bufoff) + ldsw + _i * 8192), 16, 0, 0); } while (0)
; #define PG8_LDA(dst, b, h) do { _Pragma("unroll") for (int m = 0; m < 4; ++m) _Pragma("unroll") for (int k = 0; k < 2; ++k) dst[m][k] = *(const LAS bf16x8*)(lds + PG8_SA(b, h) + aoff + m * 2048 + k * 1024); } while (0)
; #define PG8_LDB(dst, b, h) do { _Pragma("unroll") for (int n = 0; n < 2; ++n) _Pragma("unroll") for (int k = 0; k < 2; ++k) dst[n][k] = *(const LAS bf16x8*)(lds + PG8_SB(b, h) + boff + n * 2048 + k * 1024); } while (0)
; #define PG8_MMA(ai, bj, At, Bt) do { __builtin_amdgcn_s_setprio(1); _Pragma("unroll") for (int m = 0; m < 4; ++m) _Pragma("unroll") for (int n = 0; n < 2; ++n) _Pragma("unroll") for (int k = 0; k < 2; ++k) \
;     acc[ai][bj][m][n] = __builtin_amdgcn_mfma_f32_16x16x32_bf16(Bt[n][k], At[m][k], acc[ai][bj][m][n], 0, 0, 0); __builtin_amdgcn_s_setprio(0); } while (0)
; #define PG8_WAIT_V(n) asm volatile("s_waitcnt vmcnt(" #n ")" ::: "memory")
; #define PG8_WAIT_L(n) asm volatile("s_waitcnt lgkmcnt(" #n ")" ::: "memory")
; #define PG8_BAR __builtin_amdgcn_s_barrier()
; #define PG8_SCHED __builtin_amdgcn_sched_barrier(0)
; template <class Epi>
; __device__ __forceinline__ void gemm_phase(LAS unsigned char* lds, const Gemm g, const StaticOrder& S, const Epi& E) {
;     ...
;       PG8_WAIT_V(6); PG8_BAR; PG8_MMA(1, 1, At, B1); PG8_BAR;
;       PG8_LDB(B0, 1, 0); PG8_SCHED; PG8_LDA(At, 1, 0); PG8_STAGE(PG8_SA(0, 1), a2 + hstepA, voffA);
;       PG8_WAIT_L(8); PG8_BAR; PG8_WAIT_L(0); PG8_MMA(0, 0, At, B0); PG8_BAR; PG8_SCHED;
;       PG8_LDB(B1, 1, 1); PG8_STAGE(PG8_SB(1, 0), b3, voffB);
;       PG8_BAR; PG8_WAIT_L(0); PG8_MMA(0, 1, At, B1); PG8_BAR;
;       PG8_LDA(At, 1, 1); PG8_STAGE(PG8_SA(1, 0), a3, voffA);
;       PG8_BAR; PG8_WAIT_L(0); PG8_MMA(1, 0, At, B0); PG8_BAR; PG8_SCHED;
	s_add_u32 s50, s20, 0x20000
	s_addc_u32 s51, s21, 0
	s_add_i32 s25, s49, s31
	v_lshl_add_u64 v[130:131], s[50:51], 0, v[168:169]
	s_mov_b32 m0, s25
	s_nop 0
	global_load_lds_dwordx4 v[130:131], off
	v_lshl_add_u64 v[130:131], s[50:51], 0, v[164:165]
	s_add_i32 m0, s25, 0x2000
	s_nop 0
	global_load_lds_dwordx4 v[130:131], off
	s_waitcnt vmcnt(6)
	s_barrier
	s_setprio 1
	v_mfma_f32_16x16x32_bf16 v[54:57], v[198:201], v[146:149], v[54:57]
	v_mfma_f32_16x16x32_bf16 v[50:53], v[210:213], v[146:149], v[50:53]
	v_mfma_f32_16x16x32_bf16 v[38:41], v[198:201], v[154:157], v[38:41]
	v_mfma_f32_16x16x32_bf16 v[34:37], v[210:213], v[154:157], v[34:37]
	v_mfma_f32_16x16x32_bf16 v[22:25], v[198:201], v[178:181], v[22:25]
	v_mfma_f32_16x16x32_bf16 v[18:21], v[210:213], v[178:181], v[18:21]
	v_mfma_f32_16x16x32_bf16 v[4:7], v[198:201], v[186:189], v[4:7]
	v_mfma_f32_16x16x32_bf16 v[0:3], v[210:213], v[186:189], v[0:3]
	v_mfma_f32_16x16x32_bf16 v[54:57], v[206:209], v[150:153], v[54:57]
	v_mfma_f32_16x16x32_bf16 v[50:53], v[214:217], v[150:153], v[50:53]
	v_mfma_f32_16x16x32_bf16 v[38:41], v[206:209], v[158:161], v[38:41]
	v_mfma_f32_16x16x32_bf16 v[34:37], v[214:217], v[158:161], v[34:37]
	v_mfma_f32_16x16x32_bf16 v[22:25], v[206:209], v[182:185], v[22:25]
	v_mfma_f32_16x16x32_bf16 v[18:21], v[214:217], v[182:185], v[18:21]
	v_mfma_f32_16x16x32_bf16 v[4:7], v[206:209], v[190:193], v[4:7]
	v_mfma_f32_16x16x32_bf16 v[0:3], v[214:217], v[190:193], v[0:3]
	s_setprio 0
	s_add_i32 s25, 0, 0x18000
	v_add_u32_e32 v142, s25, v196
	s_barrier
	ds_read_b128 v[130:133], v142
	ds_read_b128 v[134:137], v142 offset:1024
	ds_read_b128 v[138:141], v142 offset:2048
	ds_read_b128 v[142:145], v142 offset:3072
	s_add_u32 s22, s22, 0x20000
	s_addc_u32 s23, s23, 0
	s_mov_b32 m0, s36
	v_lshl_add_u64 v[198:199], s[22:23], 0, v[170:171]
	ds_read_b128 v[146:149], v204 offset:32768
	ds_read_b128 v[150:153], v204 offset:33792
	ds_read_b128 v[154:157], v204 offset:34816
	ds_read_b128 v[158:161], v204 offset:35840
	ds_read_b128 v[178:181], v204 offset:36864
	ds_read_b128 v[182:185], v204 offset:37888
	ds_read_b128 v[186:189], v204 offset:38912
	ds_read_b128 v[190:193], v204 offset:39936
	global_load_lds_dwordx4 v[198:199], off
	v_lshl_add_u64 v[198:199], s[22:23], 0, v[166:167]
	s_mov_b32 m0, s37
	s_nop 0
	global_load_lds_dwordx4 v[198:199], off
	s_waitcnt lgkmcnt(8)
	s_barrier
	s_waitcnt lgkmcnt(0)
	s_setprio 1
	s_waitcnt lgkmcnt(0)
	v_mfma_f32_16x16x32_bf16 v[126:129], v[130:133], v[146:149], v[126:129]
	v_mfma_f32_16x16x32_bf16 v[122:125], v[138:141], v[146:149], v[122:125]
	v_mfma_f32_16x16x32_bf16 v[110:113], v[130:133], v[154:157], v[110:113]
	v_mfma_f32_16x16x32_bf16 v[106:109], v[138:141], v[154:157], v[106:109]
	v_mfma_f32_16x16x32_bf16 v[94:97], v[130:133], v[178:181], v[94:97]
	v_mfma_f32_16x16x32_bf16 v[90:93], v[138:141], v[178:181], v[90:93]
	v_mfma_f32_16x16x32_bf16 v[78:81], v[130:133], v[186:189], v[78:81]
	v_mfma_f32_16x16x32_bf16 v[74:77], v[138:141], v[186:189], v[74:77]
	v_mfma_f32_16x16x32_bf16 v[126:129], v[134:137], v[150:153], v[126:129]
	v_mfma_f32_16x16x32_bf16 v[122:125], v[142:145], v[150:153], v[122:125]
	v_mfma_f32_16x16x32_bf16 v[110:113], v[134:137], v[158:161], v[110:113]
	v_mfma_f32_16x16x32_bf16 v[106:109], v[142:145], v[158:161], v[106:109]
	v_mfma_f32_16x16x32_bf16 v[94:97], v[134:137], v[182:185], v[94:97]
	v_mfma_f32_16x16x32_bf16 v[90:93], v[142:145], v[182:185], v[90:93]
	v_mfma_f32_16x16x32_bf16 v[78:81], v[134:137], v[190:193], v[78:81]
	v_mfma_f32_16x16x32_bf16 v[74:77], v[142:145], v[190:193], v[74:77]
	s_setprio 0
	s_barrier
	s_add_i32 s22, 0, 0x1c000
	s_add_i32 s23, s25, s31
	v_add_u32_e32 v205, s22, v196
	v_lshl_add_u64 v[162:163], v[162:163], 0, s[16:17]
	s_mov_b32 m0, s23
	ds_read_b128 v[198:201], v205
	ds_read_b128 v[206:209], v205 offset:1024
	ds_read_b128 v[210:213], v205 offset:2048
	ds_read_b128 v[214:217], v205 offset:3072
	global_load_lds_dwordx4 v[162:163], off
	v_lshl_add_u64 v[162:163], v[194:195], 0, s[16:17]
	s_add_i32 m0, s23, 0x2000
	s_nop 0
	global_load_lds_dwordx4 v[162:163], off
	s_barrier
	s_waitcnt lgkmcnt(0)
	s_setprio 1
	s_waitcnt lgkmcnt(0)
	v_mfma_f32_16x16x32_bf16 v[118:121], v[198:201], v[146:149], v[118:121]
	v_mfma_f32_16x16x32_bf16 v[114:117], v[210:213], v[146:149], v[114:117]
	v_mfma_f32_16x16x32_bf16 v[102:105], v[198:201], v[154:157], v[102:105]
	v_mfma_f32_16x16x32_bf16 v[98:101], v[210:213], v[154:157], v[98:101]
	v_mfma_f32_16x16x32_bf16 v[86:89], v[198:201], v[178:181], v[86:89]
	v_mfma_f32_16x16x32_bf16 v[82:85], v[210:213], v[178:181], v[82:85]
	v_mfma_f32_16x16x32_bf16 v[70:73], v[198:201], v[186:189], v[70:73]
	v_mfma_f32_16x16x32_bf16 v[66:69], v[210:213], v[186:189], v[66:69]
	v_mfma_f32_16x16x32_bf16 v[118:121], v[206:209], v[150:153], v[118:121]
	v_mfma_f32_16x16x32_bf16 v[114:117], v[214:217], v[150:153], v[114:117]
	v_mfma_f32_16x16x32_bf16 v[102:105], v[206:209], v[158:161], v[102:105]
	v_mfma_f32_16x16x32_bf16 v[98:101], v[214:217], v[158:161], v[98:101]
	v_mfma_f32_16x16x32_bf16 v[86:89], v[206:209], v[182:185], v[86:89]
	v_mfma_f32_16x16x32_bf16 v[82:85], v[214:217], v[182:185], v[82:85]
	v_mfma_f32_16x16x32_bf16 v[70:73], v[206:209], v[190:193], v[70:73]
	v_mfma_f32_16x16x32_bf16 v[66:69], v[214:217], v[190:193], v[66:69]
	s_setprio 0
	s_mov_b32 m0, s42
	v_lshl_add_u64 v[162:163], v[218:219], 0, s[16:17]
	s_barrier
	ds_read_b128 v[146:149], v204 offset:49152
	ds_read_b128 v[150:153], v204 offset:50176
	ds_read_b128 v[154:157], v204 offset:51200
	ds_read_b128 v[158:161], v204 offset:52224
	ds_read_b128 v[178:181], v204 offset:53248
	ds_read_b128 v[182:185], v204 offset:54272
	ds_read_b128 v[186:189], v204 offset:55296
	ds_read_b128 v[190:193], v204 offset:56320
	global_load_lds_dwordx4 v[162:163], off
	v_lshl_add_u64 v[162:163], v[220:221], 0, s[16:17]
	s_mov_b32 m0, s43
	s_nop 0
	global_load_lds_dwordx4 v[162:163], off
	s_barrier
; #define PG8_STAGE(bufoff, gbase, voff) do { _Pragma("unroll") for (int _i = 0; _i < 2; ++_i) \
;     __builtin_amdgcn_global_load_lds((const unsigned*)((const char*)(gbase) + (voff)[_i]), (LAS unsigned*)(lds + (bufoff) + ldsw + _i * 8192), 16, 0, 0); } while (0)
; #define PG8_MMA(ai, bj, At, Bt) do { __builtin_amdgcn_s_setprio(1); _Pragma("unroll") for (int m = 0; m < 4; ++m) _Pragma("unroll") for (int n = 0; n < 2; ++n) _Pragma("unroll") for (int k = 0; k < 2; ++k) \
;     acc[ai][bj][m][n] = __builtin_amdgcn_mfma_f32_16x16x32_bf16(Bt[n][k], At[m][k], acc[ai][bj][m][n], 0, 0, 0); __builtin_amdgcn_s_setprio(0); } while (0)
; #define PG8_WAIT_V(n) asm volatile("s_waitcnt vmcnt(" #n ")" ::: "memory")
; #define PG8_WAIT_L(n) asm volatile("s_waitcnt lgkmcnt(" #n ")" ::: "memory")
; #define PG8_BAR __builtin_amdgcn_s_barrier()
; #define PG8_SCHED __builtin_amdgcn_sched_barrier(0)
; template <class Epi>
; __device__ __forceinline__ void gemm_phase(LAS unsigned char* lds, const Gemm g, const StaticOrder& S, const Epi& E) {
;     ...
;       PG8_BAR; PG8_WAIT_L(0); PG8_MMA(1, 0, At, B0); PG8_BAR; PG8_SCHED;
;       PG8_STAGE(PG8_SB(1, 1), b3 + hstepB, voffB);
;       PG8_WAIT_V(6); PG8_BAR; PG8_MMA(1, 1, At, B1); PG8_BAR;
;     }
	s_waitcnt lgkmcnt(0)
	s_setprio 1
	s_waitcnt lgkmcnt(0)
	v_mfma_f32_16x16x32_bf16 v[62:65], v[130:133], v[146:149], v[62:65]
	v_mfma_f32_16x16x32_bf16 v[58:61], v[138:141], v[146:149], v[58:61]
	v_mfma_f32_16x16x32_bf16 v[46:49], v[130:133], v[154:157], v[46:49]
	v_mfma_f32_16x16x32_bf16 v[42:45], v[138:141], v[154:157], v[42:45]
	v_mfma_f32_16x16x32_bf16 v[30:33], v[130:133], v[178:181], v[30:33]
	v_mfma_f32_16x16x32_bf16 v[26:29], v[138:141], v[178:181], v[26:29]
	v_mfma_f32_16x16x32_bf16 v[12:15], v[130:133], v[186:189], v[12:15]
	v_mfma_f32_16x16x32_bf16 v[8:11], v[138:141], v[186:189], v[8:11]
	v_mfma_f32_16x16x32_bf16 v[62:65], v[134:137], v[150:153], v[62:65]
	v_mfma_f32_16x16x32_bf16 v[58:61], v[142:145], v[150:153], v[58:61]
	v_mfma_f32_16x16x32_bf16 v[46:49], v[134:137], v[158:161], v[46:49]
	v_mfma_f32_16x16x32_bf16 v[42:45], v[142:145], v[158:161], v[42:45]
	v_mfma_f32_16x16x32_bf16 v[30:33], v[134:137], v[182:185], v[30:33]
	v_mfma_f32_16x16x32_bf16 v[26:29], v[142:145], v[182:185], v[26:29]
	v_mfma_f32_16x16x32_bf16 v[12:15], v[134:137], v[190:193], v[12:15]
	v_mfma_f32_16x16x32_bf16 v[8:11], v[142:145], v[190:193], v[8:11]
	s_setprio 0
	s_barrier
	s_add_u32 s20, s20, 0x20080
	s_addc_u32 s21, s21, 0
	s_add_i32 s22, s22, s31
	v_lshl_add_u64 v[130:131], s[20:21], 0, v[168:169]
	s_mov_b32 m0, s22
	s_nop 0
	global_load_lds_dwordx4 v[130:131], off
	v_lshl_add_u64 v[130:131], s[20:21], 0, v[164:165]
	s_add_i32 m0, s22, 0x2000
	s_nop 0
	global_load_lds_dwordx4 v[130:131], off
	s_waitcnt vmcnt(6)
	s_barrier
	s_setprio 1
	v_mfma_f32_16x16x32_bf16 v[54:57], v[198:201], v[146:149], v[54:57]
	v_mfma_f32_16x16x32_bf16 v[50:53], v[210:213], v[146:149], v[50:53]
	v_mfma_f32_16x16x32_bf16 v[38:41], v[198:201], v[154:157], v[38:41]
	v_mfma_f32_16x16x32_bf16 v[34:37], v[210:213], v[154:157], v[34:37]
	v_mfma_f32_16x16x32_bf16 v[22:25], v[198:201], v[178:181], v[22:25]
	v_mfma_f32_16x16x32_bf16 v[18:21], v[210:213], v[178:181], v[18:21]
	v_mfma_f32_16x16x32_bf16 v[4:7], v[198:201], v[186:189], v[4:7]
	v_mfma_f32_16x16x32_bf16 v[0:3], v[210:213], v[186:189], v[0:3]
	v_mfma_f32_16x16x32_bf16 v[54:57], v[206:209], v[150:153], v[54:57]
	v_mfma_f32_16x16x32_bf16 v[50:53], v[214:217], v[150:153], v[50:53]
	v_mfma_f32_16x16x32_bf16 v[38:41], v[206:209], v[158:161], v[38:41]
	v_mfma_f32_16x16x32_bf16 v[34:37], v[214:217], v[158:161], v[34:37]
	v_mfma_f32_16x16x32_bf16 v[22:25], v[206:209], v[182:185], v[22:25]
	v_mfma_f32_16x16x32_bf16 v[18:21], v[214:217], v[182:185], v[18:21]
	v_mfma_f32_16x16x32_bf16 v[4:7], v[206:209], v[190:193], v[4:7]
	v_mfma_f32_16x16x32_bf16 v[0:3], v[214:217], v[190:193], v[0:3]
	s_setprio 0
	s_add_i32 s24, s24, 2
	s_add_u32 s0, s0, 0x100
	s_addc_u32 s1, s1, 0
	s_add_u32 s7, s7, 0x100
	s_addc_u32 s9, s9, 0
	s_cmp_gt_u32 s24, 5
	s_barrier
	s_cbranch_scc0 .LBB0_3542
;   __device__ __forceinline__ void operator()(const f32x4 (&acc)[2][2][4][2], const Unit& u, int wr, int wc, int fr, int fq) const {
;     const unsigned char* gate = u.which ? gb : ga;
; #pragma unroll
;     for (int ai = 0; ai < 2; ++ai) {
;       u32x2 gw[4][2];
;       u32x4 pw[4][2];
; #pragma unroll
;       for (int m = 0; m < 4; ++m)
; #pragma unroll
;         for (int bj = 0; bj < 2; ++bj) {
;           const size_t o = (size_t)(u.pm * 256 + ai * 128 + wr * 64 + m * 16 + fr) * 1024 + u.pn * 256 + bj * 128 + wc * 32 + 8 * fq;
;           gw[m][bj] = *(const u32x2*)(gate + o);
;           pw[m][bj] = (u32x4){0u, 0u, 0u, 0u};
;           if (u.which) pw[m][bj] = *(const u32x4*)(mrg + o);
	s_nop 7
	v_and_b32_e32 v205, 3, v252
	v_lshlrev_b32_e32 v205, 4, v205
	v_and_b32_e32 v206, 12, v252
	v_bfe_u32 v207, v252, 4, 2
	v_or3_b32 v205, v205, v206, v207
	v_lshlrev_b32_e32 v205, 2, v205
	ds_bpermute_b32 v129, v205, v129
	ds_bpermute_b32 v128, v205, v128
	ds_bpermute_b32 v127, v205, v127
	ds_bpermute_b32 v126, v205, v126
	ds_bpermute_b32 v125, v205, v125
	ds_bpermute_b32 v124, v205, v124
	ds_bpermute_b32 v123, v205, v123
	ds_bpermute_b32 v122, v205, v122
	ds_bpermute_b32 v121, v205, v121
	ds_bpermute_b32 v120, v205, v120
	ds_bpermute_b32 v119, v205, v119
	ds_bpermute_b32 v118, v205, v118
	s_waitcnt lgkmcnt(0)
	ds_bpermute_b32 v117, v205, v117
	ds_bpermute_b32 v116, v205, v116
	ds_bpermute_b32 v115, v205, v115
	ds_bpermute_b32 v114, v205, v114
	ds_bpermute_b32 v113, v205, v113
	ds_bpermute_b32 v112, v205, v112
	ds_bpermute_b32 v111, v205, v111
	ds_bpermute_b32 v110, v205, v110
	ds_bpermute_b32 v109, v205, v109
	ds_bpermute_b32 v108, v205, v108
	ds_bpermute_b32 v107, v205, v107
	ds_bpermute_b32 v106, v205, v106
	s_waitcnt lgkmcnt(0)
	ds_bpermute_b32 v105, v205, v105
	ds_bpermute_b32 v104, v205, v104
	ds_bpermute_b32 v103, v205, v103
	ds_bpermute_b32 v102, v205, v102
	ds_bpermute_b32 v101, v205, v101
	ds_bpermute_b32 v100, v205, v100
	ds_bpermute_b32 v99, v205, v99
	ds_bpermute_b32 v98, v205, v98
	ds_bpermute_b32 v97, v205, v97
	ds_bpermute_b32 v96, v205, v96
	ds_bpermute_b32 v95, v205, v95
	ds_bpermute_b32 v94, v205, v94
	s_waitcnt lgkmcnt(0)
	ds_bpermute_b32 v93, v205, v93
	ds_bpermute_b32 v92, v205, v92
	ds_bpermute_b32 v91, v205, v91
	ds_bpermute_b32 v90, v205, v90
	ds_bpermute_b32 v89, v205, v89
	ds_bpermute_b32 v88, v205, v88
	ds_bpermute_b32 v87, v205, v87
	ds_bpermute_b32 v86, v205, v86
	ds_bpermute_b32 v85, v205, v85
	ds_bpermute_b32 v84, v205, v84
	ds_bpermute_b32 v83, v205, v83
	ds_bpermute_b32 v82, v205, v82
	s_waitcnt lgkmcnt(0)
	ds_bpermute_b32 v81, v205, v81
	ds_bpermute_b32 v80, v205, v80
	ds_bpermute_b32 v79, v205, v79
	ds_bpermute_b32 v78, v205, v78
	ds_bpermute_b32 v77, v205, v77
	ds_bpermute_b32 v76, v205, v76
	ds_bpermute_b32 v75, v205, v75
	ds_bpermute_b32 v74, v205, v74
	ds_bpermute_b32 v73, v205, v73
	ds_bpermute_b32 v72, v205, v72
	ds_bpermute_b32 v71, v205, v71
	ds_bpermute_b32 v70, v205, v70
	s_waitcnt lgkmcnt(0)
	ds_bpermute_b32 v69, v205, v69
	ds_bpermute_b32 v68, v205, v68
	ds_bpermute_b32 v67, v205, v67
	ds_bpermute_b32 v66, v205, v66
	ds_bpermute_b32 v65, v205, v65
	ds_bpermute_b32 v64, v205, v64
	ds_bpermute_b32 v63, v205, v63
	ds_bpermute_b32 v62, v205, v62
	ds_bpermute_b32 v61, v205, v61
	ds_bpermute_b32 v60, v205, v60
	ds_bpermute_b32 v59, v205, v59
	ds_bpermute_b32 v58, v205, v58
	s_waitcnt lgkmcnt(0)
	ds_bpermute_b32 v57, v205, v57
	ds_bpermute_b32 v56, v205, v56
	ds_bpermute_b32 v55, v205, v55
	ds_bpermute_b32 v54, v205, v54
	ds_bpermute_b32 v53, v205, v53
	ds_bpermute_b32 v52, v205, v52
	ds_bpermute_b32 v51, v205, v51
	ds_bpermute_b32 v50, v205, v50
	ds_bpermute_b32 v49, v205, v49
	ds_bpermute_b32 v48, v205, v48
	ds_bpermute_b32 v47, v205, v47
	ds_bpermute_b32 v46, v205, v46
	s_waitcnt lgkmcnt(0)
	ds_bpermute_b32 v45, v205, v45
	ds_bpermute_b32 v44, v205, v44
	ds_bpermute_b32 v43, v205, v43
	ds_bpermute_b32 v42, v205, v42
	ds_bpermute_b32 v41, v205, v41
	ds_bpermute_b32 v40, v205, v40
	ds_bpermute_b32 v39, v205, v39
	ds_bpermute_b32 v38, v205, v38
	ds_bpermute_b32 v37, v205, v37
	ds_bpermute_b32 v36, v205, v36
	ds_bpermute_b32 v35, v205, v35
	ds_bpermute_b32 v34, v205, v34
	s_waitcnt lgkmcnt(0)
	ds_bpermute_b32 v33, v205, v33
	ds_bpermute_b32 v32, v205, v32
	ds_bpermute_b32 v31, v205, v31
	ds_bpermute_b32 v30, v205, v30
	ds_bpermute_b32 v29, v205, v29
	ds_bpermute_b32 v28, v205, v28
	ds_bpermute_b32 v27, v205, v27
	ds_bpermute_b32 v26, v205, v26
	ds_bpermute_b32 v25, v205, v25
	ds_bpermute_b32 v24, v205, v24
	ds_bpermute_b32 v23, v205, v23
	ds_bpermute_b32 v22, v205, v22
	s_waitcnt lgkmcnt(0)
	ds_bpermute_b32 v21, v205, v21
	ds_bpermute_b32 v20, v205, v20
	ds_bpermute_b32 v19, v205, v19
	ds_bpermute_b32 v18, v205, v18
	ds_bpermute_b32 v15, v205, v15
	ds_bpermute_b32 v14, v205, v14
	ds_bpermute_b32 v13, v205, v13
	ds_bpermute_b32 v12, v205, v12
	ds_bpermute_b32 v11, v205, v11
	ds_bpermute_b32 v10, v205, v10
	ds_bpermute_b32 v9, v205, v9
	ds_bpermute_b32 v8, v205, v8
	s_waitcnt lgkmcnt(0)
	ds_bpermute_b32 v7, v205, v7
	ds_bpermute_b32 v6, v205, v6
	ds_bpermute_b32 v5, v205, v5
	ds_bpermute_b32 v4, v205, v4
	ds_bpermute_b32 v3, v205, v3
	ds_bpermute_b32 v2, v205, v2
	ds_bpermute_b32 v1, v205, v1
	ds_bpermute_b32 v0, v205, v0
	s_waitcnt lgkmcnt(0)
	s_cmp_lg_u32 s48, 0
	s_cselect_b64 s[24:25], -1, 0
	s_cmp_eq_u32 s48, 0
	s_cselect_b64 s[0:1], -1, 0
	s_and_b64 vcc, s[0:1], exec
	s_mov_b32 s0, 0x10922000
	s_cselect_b32 s0, s0, 0x14a22000
	s_add_u32 s22, s2, s0
	s_addc_u32 s23, s3, 0
	s_lshl_b32 s7, s47, 8
	v_add_u32_e32 v178, s7, v173
	s_lshl_b32 s20, s46, 8
	s_ashr_i32 s21, s20, 31
	v_ashrrev_i32_e32 v179, 31, v178
	v_mov_b32_e32 v181, s21
	v_or_b32_e32 v180, s20, v172
	v_lshlrev_b64 v[130:131], 10, v[178:179]
	v_lshl_add_u64 v[130:131], v[130:131], 0, v[180:181]
	v_lshl_add_u64 v[132:133], s[22:23], 0, v[130:131]
	global_load_dwordx2 v[198:199], v[132:133], off
	v_mov_b32_e32 v148, 0
	v_mov_b32_e32 v160, 0
	v_mov_b32_e32 v161, 0
	v_mov_b32_e32 v162, 0
	v_mov_b32_e32 v163, 0
	s_cbranch_vccnz .LBB0_3545
	v_lshl_add_u64 v[134:135], v[130:131], 1, s[4:5]
	global_load_dwordx4 v[160:163], v[134:135], off
